# v55 + rglru even steps: conv waits count the six younger stores (vmcnt+6), prefetch-block reuse waits skipped on that path
# baseline (speedup 1.0000x reference)
.LBB0_355:
	s_cmp_gt_u32 s94, 1
	s_cselect_b64 s[12:13], -1, 0
	s_lshl_b32 s14, s94, 7
	s_and_b32 s14, s14, 0x1f00
	s_addk_i32 s14, 0xff00
	s_cmp_lt_u32 s94, 2
	s_cselect_b32 s14, 0, s14
	s_cselect_b32 s54, 0x100, s58
	s_lshl_b32 s15, s94, 4
	s_add_i32 s14, s14, s85
	s_and_b32 s15, s15, 16
	s_or_b32 s14, s14, s15
	v_or_b32_e32 v0, s14, v236
	ds_read_b128 v[128:131], v241 offset:38400
	ds_read_b128 v[124:127], v241 offset:38416
	v_xad_u32 v122, v0, -1, s54
	v_cndmask_b32_e64 v246, v122, v0, s[44:45]
	v_add_u32_e32 v123, -2, v246
	s_add_i32 s15, s54, -4
	v_cmp_ge_u32_e32 vcc, s15, v123
	s_nop 0
	s_mov_b32 s101, 0
	s_nop 0
	s_cmp_eq_u64 vcc, exec
	s_cbranch_scc1 .Lrg_fast
	s_or_b32 s14, s54, 2
	v_cmp_lt_i32_e32 vcc, 1, v246
	v_cmp_gt_i32_e64 s[52:53], s14, v246
	s_and_b64 s[14:15], vcc, s[52:53]
	s_and_saveexec_b64 s[16:17], s[14:15]
	s_cbranch_execz .LBB0_357
	ds_read_b128 v[132:135], v241 offset:36864
	ds_read_b128 v[136:139], v241 offset:36880
	s_waitcnt vmcnt(11)
	v_lshlrev_b32_e32 v122, 16, v2
	v_and_b32_e32 v123, 0xffff0000, v2
	s_waitcnt lgkmcnt(1)
	v_pk_fma_f32 v[128:129], v[132:133], v[122:123], v[128:129]
	v_lshlrev_b32_e32 v122, 16, v3
	v_and_b32_e32 v123, 0xffff0000, v3
	v_pk_fma_f32 v[130:131], v[134:135], v[122:123], v[130:131]
	v_lshlrev_b32_e32 v122, 16, v4
	v_and_b32_e32 v123, 0xffff0000, v4
	s_waitcnt lgkmcnt(0)
	v_pk_fma_f32 v[124:125], v[136:137], v[122:123], v[124:125]
	v_lshlrev_b32_e32 v122, 16, v5
	v_and_b32_e32 v123, 0xffff0000, v5
	v_pk_fma_f32 v[126:127], v[138:139], v[122:123], v[126:127]

.LBB0_381:
	s_or_b64 exec, exec, s[52:53]
	s_add_i32 s18, s94, 1
	s_cmp_eq_u32 s94, 33
	s_cbranch_scc1 .LBB0_399
	s_cmp_lg_u32 s94, 0
	s_cselect_b64 s[14:15], -1, 0
	s_lshl_b32 s16, s18, 7
	s_and_b32 s16, s16, 0x3f00
	s_addk_i32 s16, 0xff00
	s_cmp_eq_u32 s94, 0
	s_cselect_b32 s16, 0, s16
	s_cselect_b32 s19, 0x100, s58
	s_lshl_b32 s17, s18, 4
	s_add_i32 s16, s16, s85
	s_and_b32 s17, s17, 16
	s_or_b32 s16, s16, s17
	v_or_b32_e32 v0, s16, v236
	s_cmp_eq_u32 s101, 1
	s_cbranch_scc1 .Lrg_sk1
	s_waitcnt vmcnt(11)
.Lrg_sk1:
	v_xad_u32 v2, v0, -1, s19
	s_cbranch_scc1 .Lrg_sk2
	s_waitcnt vmcnt(2)
.Lrg_sk2:
	s_nop 0
	v_cndmask_b32_e64 v38, v2, v0, s[44:45]
	s_add_i32 s19, s19, -1
	v_add_u32_e32 v0, -2, v38
	v_min_i32_e32 v0, s19, v0
	v_cmp_lt_i32_e32 vcc, 1, v38
	s_mov_b64 s[16:17], -1
	s_nop 0
	v_cndmask_b32_e32 v0, 0, v0, vcc
	s_and_b64 vcc, exec, s[14:15]
	s_cbranch_vccz .LBB0_384
	v_lshlrev_b32_e32 v2, 6, v0
	v_and_b32_e32 v2, 0xfc0, v2
	v_ashrrev_i32_e32 v3, 6, v0
	v_add_u32_e32 v2, v2, v3
	v_cndmask_b32_e64 v2, v2, v0, s[42:43]
	v_add_u32_e32 v2, s40, v2
	s_mov_b64 s[16:17], 0

.LBB0_398:
	v_mov_b64_e32 v[40:41], s[78:79]
	s_cmp_eq_u32 s101, 1
	s_cbranch_scc1 .Lrg_sk3
	s_waitcnt vmcnt(9)
.Lrg_sk3:
	v_mad_i64_i32 v[46:47], s[14:15], v39, s91, v[40:41]
	v_mov_b32_e32 v175, v1
	v_lshl_add_u64 v[42:43], v[46:47], 0, v[0:1]
	v_lshl_add_u64 v[46:47], v[46:47], 0, v[174:175]
	global_load_dwordx4 v[38:41], v[42:43], off
	s_nop 0
	global_load_dwordx4 v[42:45], v[42:43], off offset:64
	s_nop 0
	global_load_dwordx4 v[46:49], v[46:47], off

.Lrg_fast:
	s_bitcmp1_b32 s94, 0
	s_cbranch_scc1 .Lrg_fast_o
	s_cmp_lg_u32 s94, 0
	s_cbranch_scc1 .Lrg_fast_e

.Lrg_fast_e:
	s_mov_b32 s101, 1
	ds_read_b128 v[132:135], v241 offset:36864
	ds_read_b128 v[136:139], v241 offset:36880
	ds_read_b128 v[140:143], v241 offset:37248
	ds_read_b128 v[144:147], v241 offset:37264
	s_waitcnt vmcnt(17) lgkmcnt(2)
	v_lshlrev_b32_e32 v122, 16, v2
	v_and_b32_e32 v123, 0xffff0000, v2
	v_pk_fma_f32 v[128:129], v[132:133], v[122:123], v[128:129]
	v_lshlrev_b32_e32 v122, 16, v3
	v_and_b32_e32 v123, 0xffff0000, v3
	v_pk_fma_f32 v[130:131], v[134:135], v[122:123], v[130:131]
	v_lshlrev_b32_e32 v122, 16, v4
	v_and_b32_e32 v123, 0xffff0000, v4
	v_pk_fma_f32 v[124:125], v[136:137], v[122:123], v[124:125]
	v_lshlrev_b32_e32 v122, 16, v5
	v_and_b32_e32 v123, 0xffff0000, v5
	v_pk_fma_f32 v[126:127], v[138:139], v[122:123], v[126:127]
	ds_read_b128 v[132:135], v241 offset:37632
	ds_read_b128 v[136:139], v241 offset:37648
	s_waitcnt vmcnt(14) lgkmcnt(2)
	v_lshlrev_b32_e32 v122, 16, v14
	v_and_b32_e32 v123, 0xffff0000, v14
	v_pk_fma_f32 v[128:129], v[140:141], v[122:123], v[128:129]
	v_lshlrev_b32_e32 v122, 16, v15
	v_and_b32_e32 v123, 0xffff0000, v15
	v_pk_fma_f32 v[130:131], v[142:143], v[122:123], v[130:131]
	v_lshlrev_b32_e32 v122, 16, v16
	v_and_b32_e32 v123, 0xffff0000, v16
	v_pk_fma_f32 v[124:125], v[144:145], v[122:123], v[124:125]
	v_lshlrev_b32_e32 v122, 16, v17
	v_and_b32_e32 v123, 0xffff0000, v17
	v_pk_fma_f32 v[126:127], v[146:147], v[122:123], v[126:127]
	ds_read_b128 v[140:143], v241 offset:38016
	ds_read_b128 v[144:147], v241 offset:38032
	s_waitcnt vmcnt(11) lgkmcnt(2)
	v_lshlrev_b32_e32 v122, 16, v26
	v_and_b32_e32 v123, 0xffff0000, v26
	v_pk_fma_f32 v[128:129], v[132:133], v[122:123], v[128:129]
	v_lshlrev_b32_e32 v122, 16, v27
	v_and_b32_e32 v123, 0xffff0000, v27
	v_pk_fma_f32 v[130:131], v[134:135], v[122:123], v[130:131]
	v_lshlrev_b32_e32 v122, 16, v28
	v_and_b32_e32 v123, 0xffff0000, v28
	v_pk_fma_f32 v[124:125], v[136:137], v[122:123], v[124:125]
	v_lshlrev_b32_e32 v122, 16, v29
	v_and_b32_e32 v123, 0xffff0000, v29
	v_pk_fma_f32 v[126:127], v[138:139], v[122:123], v[126:127]
	s_waitcnt vmcnt(8) lgkmcnt(0)
	v_lshlrev_b32_e32 v122, 16, v38
	v_and_b32_e32 v123, 0xffff0000, v38
	v_pk_fma_f32 v[128:129], v[140:141], v[122:123], v[128:129]
	v_lshlrev_b32_e32 v122, 16, v39
	v_and_b32_e32 v123, 0xffff0000, v39
	v_pk_fma_f32 v[130:131], v[142:143], v[122:123], v[130:131]
	v_lshlrev_b32_e32 v122, 16, v40
	v_and_b32_e32 v123, 0xffff0000, v40
	v_pk_fma_f32 v[124:125], v[144:145], v[122:123], v[124:125]
	v_lshlrev_b32_e32 v122, 16, v41
	v_and_b32_e32 v123, 0xffff0000, v41
	v_pk_fma_f32 v[126:127], v[146:147], v[122:123], v[126:127]
	ds_write_b128 v242, v[128:131] offset:40960
	ds_write_b128 v242, v[124:127] offset:40976
	v_cvt_pk_bf16_f32 v122, v128, v129
	v_cvt_pk_bf16_f32 v123, v130, v131
	v_cvt_pk_bf16_f32 v124, v124, v125
	v_cvt_pk_bf16_f32 v125, v126, v127
	ds_read_b128 v[132:135], v241 offset:38528
	ds_read_b128 v[136:139], v241 offset:38544
	ds_read_b128 v[140:143], v241 offset:36992
	ds_read_b128 v[144:147], v241 offset:37008
	ds_read_b128 v[170:173], v241 offset:37376
	ds_read_b128 v[248:251], v241 offset:37392
	s_waitcnt vmcnt(16) lgkmcnt(2)
	v_lshlrev_b32_e32 v130, 16, v6
	v_and_b32_e32 v131, 0xffff0000, v6
	v_pk_fma_f32 v[132:133], v[140:141], v[130:131], v[132:133]
	v_lshlrev_b32_e32 v130, 16, v7
	v_and_b32_e32 v131, 0xffff0000, v7
	v_pk_fma_f32 v[134:135], v[142:143], v[130:131], v[134:135]
	v_lshlrev_b32_e32 v130, 16, v8
	v_and_b32_e32 v131, 0xffff0000, v8
	v_pk_fma_f32 v[136:137], v[144:145], v[130:131], v[136:137]
	v_lshlrev_b32_e32 v130, 16, v9
	v_and_b32_e32 v131, 0xffff0000, v9
	v_pk_fma_f32 v[138:139], v[146:147], v[130:131], v[138:139]
	ds_read_b128 v[140:143], v241 offset:37760
	ds_read_b128 v[144:147], v241 offset:37776
	s_waitcnt vmcnt(13) lgkmcnt(2)
	v_lshlrev_b32_e32 v130, 16, v18
	v_and_b32_e32 v131, 0xffff0000, v18
	v_pk_fma_f32 v[132:133], v[170:171], v[130:131], v[132:133]
	v_lshlrev_b32_e32 v130, 16, v19
	v_and_b32_e32 v131, 0xffff0000, v19
	v_pk_fma_f32 v[134:135], v[172:173], v[130:131], v[134:135]
	v_lshlrev_b32_e32 v130, 16, v20
	v_and_b32_e32 v131, 0xffff0000, v20
	v_pk_fma_f32 v[136:137], v[248:249], v[130:131], v[136:137]
	v_lshlrev_b32_e32 v130, 16, v21
	v_and_b32_e32 v131, 0xffff0000, v21
	v_pk_fma_f32 v[138:139], v[250:251], v[130:131], v[138:139]
	ds_read_b128 v[170:173], v241 offset:38144
	ds_read_b128 v[248:251], v241 offset:38160
	s_waitcnt vmcnt(10) lgkmcnt(2)
	v_lshlrev_b32_e32 v130, 16, v30
	v_and_b32_e32 v131, 0xffff0000, v30
	v_pk_fma_f32 v[132:133], v[140:141], v[130:131], v[132:133]
	v_lshlrev_b32_e32 v130, 16, v31
	v_and_b32_e32 v131, 0xffff0000, v31
	v_pk_fma_f32 v[134:135], v[142:143], v[130:131], v[134:135]
	v_lshlrev_b32_e32 v130, 16, v32
	v_and_b32_e32 v131, 0xffff0000, v32
	v_pk_fma_f32 v[136:137], v[144:145], v[130:131], v[136:137]
	v_lshlrev_b32_e32 v130, 16, v33
	v_and_b32_e32 v131, 0xffff0000, v33
	v_pk_fma_f32 v[138:139], v[146:147], v[130:131], v[138:139]
	s_waitcnt vmcnt(7) lgkmcnt(0)
	v_lshlrev_b32_e32 v130, 16, v42
	v_and_b32_e32 v131, 0xffff0000, v42
	v_pk_fma_f32 v[132:133], v[170:171], v[130:131], v[132:133]
	v_lshlrev_b32_e32 v130, 16, v43
	v_and_b32_e32 v131, 0xffff0000, v43
	v_pk_fma_f32 v[134:135], v[172:173], v[130:131], v[134:135]
	v_lshlrev_b32_e32 v130, 16, v44
	v_and_b32_e32 v131, 0xffff0000, v44
	v_pk_fma_f32 v[136:137], v[248:249], v[130:131], v[136:137]
	v_lshlrev_b32_e32 v130, 16, v45
	v_and_b32_e32 v131, 0xffff0000, v45
	v_pk_fma_f32 v[138:139], v[250:251], v[130:131], v[138:139]
	ds_write_b128 v242, v[132:135] offset:41088
	ds_write_b128 v242, v[136:139] offset:41104
	v_cvt_pk_bf16_f32 v126, v132, v133
	v_cvt_pk_bf16_f32 v127, v134, v135
	v_cvt_pk_bf16_f32 v128, v136, v137
	v_cvt_pk_bf16_f32 v129, v138, v139
	ds_read_b128 v[132:135], v241 offset:38656
	ds_read_b128 v[136:139], v241 offset:38672
	ds_read_b128 v[140:143], v241 offset:37120
	ds_read_b128 v[144:147], v241 offset:37136
	ds_read_b128 v[170:173], v241 offset:37504
	ds_read_b128 v[248:251], v241 offset:37520
	s_waitcnt vmcnt(15) lgkmcnt(2)
	v_lshlrev_b32_e32 v130, 16, v10
	v_and_b32_e32 v131, 0xffff0000, v10
	v_pk_fma_f32 v[132:133], v[140:141], v[130:131], v[132:133]
	v_lshlrev_b32_e32 v130, 16, v11
	v_and_b32_e32 v131, 0xffff0000, v11
	v_pk_fma_f32 v[134:135], v[142:143], v[130:131], v[134:135]
	v_lshlrev_b32_e32 v130, 16, v12
	v_and_b32_e32 v131, 0xffff0000, v12
	v_pk_fma_f32 v[136:137], v[144:145], v[130:131], v[136:137]
	v_lshlrev_b32_e32 v130, 16, v13
	v_and_b32_e32 v131, 0xffff0000, v13
	v_pk_fma_f32 v[138:139], v[146:147], v[130:131], v[138:139]
	ds_read_b128 v[140:143], v241 offset:37888
	ds_read_b128 v[144:147], v241 offset:37904
	s_waitcnt vmcnt(12) lgkmcnt(2)
	v_lshlrev_b32_e32 v130, 16, v22
	v_and_b32_e32 v131, 0xffff0000, v22
	v_pk_fma_f32 v[132:133], v[170:171], v[130:131], v[132:133]
	v_lshlrev_b32_e32 v130, 16, v23
	v_and_b32_e32 v131, 0xffff0000, v23
	v_pk_fma_f32 v[134:135], v[172:173], v[130:131], v[134:135]
	v_lshlrev_b32_e32 v130, 16, v24
	v_and_b32_e32 v131, 0xffff0000, v24
	v_pk_fma_f32 v[136:137], v[248:249], v[130:131], v[136:137]
	v_lshlrev_b32_e32 v130, 16, v25
	v_and_b32_e32 v131, 0xffff0000, v25
	v_pk_fma_f32 v[138:139], v[250:251], v[130:131], v[138:139]
	ds_read_b128 v[170:173], v241 offset:38272
	ds_read_b128 v[248:251], v241 offset:38288
	s_waitcnt vmcnt(9) lgkmcnt(2)
	v_lshlrev_b32_e32 v130, 16, v34
	v_and_b32_e32 v131, 0xffff0000, v34
	v_pk_fma_f32 v[132:133], v[140:141], v[130:131], v[132:133]
	v_lshlrev_b32_e32 v130, 16, v35
	v_and_b32_e32 v131, 0xffff0000, v35
	v_pk_fma_f32 v[134:135], v[142:143], v[130:131], v[134:135]
	v_lshlrev_b32_e32 v130, 16, v36
	v_and_b32_e32 v131, 0xffff0000, v36
	v_pk_fma_f32 v[136:137], v[144:145], v[130:131], v[136:137]
	v_lshlrev_b32_e32 v130, 16, v37
	v_and_b32_e32 v131, 0xffff0000, v37
	v_pk_fma_f32 v[138:139], v[146:147], v[130:131], v[138:139]
	s_waitcnt vmcnt(6) lgkmcnt(0)
	v_lshlrev_b32_e32 v130, 16, v46
	v_and_b32_e32 v131, 0xffff0000, v46
	v_pk_fma_f32 v[132:133], v[170:171], v[130:131], v[132:133]
	v_lshlrev_b32_e32 v130, 16, v47
	v_and_b32_e32 v131, 0xffff0000, v47
	v_pk_fma_f32 v[134:135], v[172:173], v[130:131], v[134:135]
	v_lshlrev_b32_e32 v130, 16, v48
	v_and_b32_e32 v131, 0xffff0000, v48
	v_pk_fma_f32 v[136:137], v[248:249], v[130:131], v[136:137]
	v_lshlrev_b32_e32 v130, 16, v49
	v_and_b32_e32 v131, 0xffff0000, v49
	v_pk_fma_f32 v[138:139], v[250:251], v[130:131], v[138:139]
	s_and_saveexec_b64 s[52:53], s[50:51]
	ds_write_b128 v242, v[132:135] offset:41216
	ds_write_b128 v242, v[136:139] offset:41232
	s_mov_b64 exec, s[52:53]
	v_cvt_pk_bf16_f32 v146, v132, v133
	v_cvt_pk_bf16_f32 v147, v134, v135
	v_cvt_pk_bf16_f32 v148, v136, v137
	v_cvt_pk_bf16_f32 v149, v138, v139
	v_cndmask_b32_e64 v146, 0, v146, s[50:51]
	v_cndmask_b32_e64 v147, 0, v147, s[50:51]
	v_cndmask_b32_e64 v148, 0, v148, s[50:51]
	v_cndmask_b32_e64 v149, 0, v149, s[50:51]
	s_branch .LBB0_381
